# v31 plus static s_setprio 1 for waves 4-7 during the scan phase as well
# speedup vs baseline: 1.0041x; 1.0041x over previous
.LBB0_53:
	s_or_b64 exec, exec, s[4:5]
	v_readfirstlane_b32 s4, v154
	s_bitcmp1_b32 s4, 8
	s_cbranch_scc0 .Lprio_scan
	s_setprio 1
.Lprio_scan:
	s_add_u32 s54, s30, 0x2300000
	s_addc_u32 s55, s31, 0
	s_add_u32 s53, s28, 0xc000000
	s_addc_u32 s59, s29, 0
	s_add_u32 s0, s30, 0x2a00000
	v_writelane_b32 v228, s0, 38
	s_addc_u32 s0, s31, 0
	v_writelane_b32 v228, s0, 39
	s_add_u32 s0, s30, 0x2400000
	v_writelane_b32 v228, s0, 40
	s_addc_u32 s0, s31, 0
	v_writelane_b32 v228, s0, 41
	s_add_i32 s1, 0, 0x15000
	v_writelane_b32 v228, s1, 42
	s_add_i32 s1, 0, 0x13500
	v_writelane_b32 v228, s1, 43
	s_add_i32 s1, 0, 0x13a00
	v_writelane_b32 v228, s1, 44
	s_add_i32 s1, 0, 0x1a000
	v_writelane_b32 v228, s1, 45
	s_add_i32 s1, 0, 0x13b00
	v_writelane_b32 v228, s1, 46
	s_add_i32 s1, 0, 0x1fa00
	v_writelane_b32 v228, s1, 47
	s_add_i32 s1, 0, 0x1b00
	v_mov_b32_e32 v134, v154
	s_add_i32 s0, 0, 0x14000
	s_movk_i32 s88, 0xe200
	v_writelane_b32 v228, s1, 48
	s_add_i32 s1, 0, 0xdb00
	s_mov_b32 s52, s33
	s_barrier
	v_mov_b32_e32 v68, 0
	v_cmp_eq_u32_e64 s[14:15], 0, v134
	s_add_i32 s56, 0, 0x13000
	s_movk_i32 s57, 0xfe00
	s_movk_i32 s33, 0x1e00
	s_mov_b32 s89, -1
	s_mov_b64 s[90:91], 0x1e00
	s_add_i32 s87, 0, 0x10100
	s_add_i32 s35, 0, 0x11300
	s_add_i32 s97, 0, 0x1c000
	v_writelane_b32 v228, s1, 49
	s_add_i32 s1, 0, 0xc200
	s_mov_b32 s58, s0
	v_mov_b32_e32 v135, s0
	v_mov_b32_e32 v136, 0xe40
	v_mov_b32_e32 v137, 0xe00
	v_writelane_b32 v228, s1, 50
	s_branch .LBB0_56
